# FFN-up phase: tiles after the first two of each workgroup are claimed from a per-XCD atomic counter (claimed two tiles ahead in the epilogue by wave 0, broadcast through LDS) instead of the static rou
# baseline (speedup 1.0000x reference)
.LBB0_450:
	s_add_i32 s71, s71, 1
	s_cmp_lt_u32 s71, 2
	s_cbranch_scc1 .Lmy_dyn_static
	s_mov_b32 s28, s101
	s_mov_b32 s29, 0
	s_branch .Lmy_dyn_have
.Lmy_dyn_static:
	s_mul_i32 s20, s71, s84
	s_mul_hi_u32 s21, s71, s34
	s_add_i32 s21, s21, s20
	s_mul_i32 s20, s71, s34
	s_add_u32 s28, s20, s2
	s_addc_u32 s29, s21, s83
.Lmy_dyn_have:
	v_mov_b64_e32 v[10:11], 0xb00
	v_cmp_lt_i64_e64 s[20:21], s[28:29], v[10:11]
	v_mov_b64_e32 v[10:11], 0xaff
	v_cmp_gt_i64_e32 vcc, s[28:29], v[10:11]
	s_cbranch_vccnz .LBB0_452
	s_ashr_i32 s29, s28, 31
	s_lshr_b32 s29, s29, 29
	s_add_i32 s29, s28, s29
	s_ashr_i32 s30, s29, 3
	s_and_b32 s29, s29, -8
	s_sub_i32 s28, s28, s29
	s_cmp_lt_i32 s28, 0
	s_movk_i32 s29, 0x161
	s_cselect_b32 s29, s29, 0x160
	s_mul_i32 s28, s28, s29
	s_add_i32 s28, s28, s30
	s_mul_hi_i32 s29, s28, 0x2e8ba2e9
	s_lshr_b32 s30, s29, 31
	s_ashr_i32 s29, s29, 5
	s_add_i32 s29, s29, s30
	s_lshl_b32 s30, s29, 3
	s_mulk_i32 s29, 0xb0
	s_sub_i32 s28, s28, s29
	s_lshr_b32 s72, s28, 3
	s_and_b32 s28, s28, 7
	s_add_i32 s74, s30, s28
	s_lshl_b32 s98, s74, 8
	s_lshl_b32 s80, s72, 8

.LBB0_456:
	v_readfirstlane_b32 s100, v237
	s_cmp_gt_u32 s100, 63
	s_cbranch_scc1 .Lmy_dyn_c1
	s_lshl_b32 s100, s40, 11
	s_and_b32 s32, s2, 7
	s_lshl_b32 s32, s32, 8
	s_add_i32 s100, s100, s32
	s_add_i32 s100, s100, 0x5000
	s_mov_b64 s[28:29], exec
	s_mov_b64 exec, 1
	v_mov_b32_e32 v250, s100
	v_mov_b32_e32 v251, 1
	global_atomic_add v251, v250, v251, s[36:37] sc0
	s_mov_b64 exec, s[28:29]
.Lmy_dyn_c1:
	s_lshl_b32 s81, s73, 8
	v_add_u32_e32 v210, s81, v219
	v_ashrrev_i32_e32 v211, 31, v210
	v_lshl_add_u64 v[106:107], v[210:211], 4, s[48:49]
	global_load_dwordx4 v[128:131], v[106:107], off
	v_or_b32_e32 v106, 16, v210
	v_ashrrev_i32_e32 v107, 31, v106
	v_lshl_add_u64 v[106:107], v[106:107], 4, s[48:49]
	global_load_dwordx4 v[164:167], v[106:107], off
	v_or_b32_e32 v106, 32, v210
	v_ashrrev_i32_e32 v107, 31, v106
	v_lshl_add_u64 v[106:107], v[106:107], 4, s[48:49]
	global_load_dwordx4 v[160:163], v[106:107], off
	v_or_b32_e32 v106, 48, v210
	v_ashrrev_i32_e32 v107, 31, v106
	v_lshl_add_u64 v[106:107], v[106:107], 4, s[48:49]
	global_load_dwordx4 v[106:109], v[106:107], off
	v_add_u32_e32 v206, 0x80, v210
	v_add_u32_e32 v198, 0xb0, v210
	v_ashrrev_i32_e32 v207, 31, v206
	v_ashrrev_i32_e32 v199, 31, v198
	v_add_u32_e32 v204, 0x90, v210
	v_ashrrev_i32_e32 v205, 31, v204
	v_add_u32_e32 v200, 0xa0, v210
	v_ashrrev_i32_e32 v201, 31, v200
	s_load_dwordx4 s[28:31], s[0:1], 0x68
	v_lshl_or_b32 v212, s68, 7, v221
	s_waitcnt vmcnt(0)
	v_readfirstlane_b32 s100, v237
	s_cmp_gt_u32 s100, 63
	s_cbranch_scc1 .Lmy_dyn_c2
	v_readfirstlane_b32 s100, v251
	v_mov_b32_e32 v250, 0x21008
	v_mov_b32_e32 v251, s100
	ds_write_b32 v250, v251
.Lmy_dyn_c2:
	v_mov_b32_e32 v110, v107
	v_mov_b32_e32 v111, v108
	v_mov_b32_e32 v107, v109
	v_pk_add_f32 v[106:107], v[110:111], v[106:107]
	v_lshl_add_u64 v[110:111], v[198:199], 4, s[48:49]
	v_add_f32_e32 v106, v106, v107
	v_fmamk_f32 v106, v106, 0x3a800000, v238
	v_rsq_f32_e32 v208, v106
	global_load_dwordx4 v[132:135], v[110:111], off
	v_pk_mul_f32 v[138:139], v[102:103], v[208:209] op_sel_hi:[1,0]
	v_lshl_add_u64 v[102:103], v[206:207], 4, s[48:49]
	global_load_dwordx4 v[112:115], v[102:103], off
	v_lshl_add_u64 v[102:103], v[204:205], 4, s[48:49]
	global_load_dwordx4 v[106:109], v[102:103], off
	v_lshl_add_u64 v[102:103], v[200:201], 4, s[48:49]
	v_pk_mul_f32 v[140:141], v[104:105], v[208:209] op_sel_hi:[1,0]
	global_load_dwordx4 v[102:105], v[102:103], off
	v_pk_mul_f32 v[56:57], v[56:57], v[208:209] op_sel_hi:[1,0]
	v_pk_mul_f32 v[54:55], v[54:55], v[208:209] op_sel_hi:[1,0]
	s_waitcnt vmcnt(3)
	v_mov_b32_e32 v110, v133
	v_mov_b32_e32 v111, v134
	v_mov_b32_e32 v133, v135
	v_pk_add_f32 v[110:111], v[110:111], v[132:133]
	s_nop 0
	v_add_f32_e32 v110, v110, v111
	v_fmamk_f32 v110, v110, 0x3a800000, v238
	v_rsq_f32_e32 v202, v110
	v_cndmask_b32_e64 v110, 0, 1, s[92:93]
	v_cmp_ne_u32_e64 s[22:23], 1, v110
	v_pk_mul_f32 v[92:93], v[92:93], v[202:203] op_sel_hi:[1,0]
	v_pk_mul_f32 v[90:91], v[90:91], v[202:203] op_sel_hi:[1,0]
	v_pk_mul_f32 v[36:37], v[36:37], v[202:203] op_sel_hi:[1,0]
	v_pk_mul_f32 v[34:35], v[34:35], v[202:203] op_sel_hi:[1,0]
	s_and_saveexec_b64 s[24:25], s[4:5]
	s_cbranch_execz .LBB0_459
	s_and_b64 vcc, exec, s[22:23]
	ds_write_b128 v222, v[138:141]
	ds_write_b128 v222, v[54:57] offset:16
	ds_write_b128 v223, v[90:93]
	ds_write_b128 v222, v[34:37] offset:2064
	s_cbranch_vccnz .LBB0_459
	v_readlane_b32 s68, v254, 9
	v_readlane_b32 s69, v254, 10
	v_lshl_add_u32 v132, s73, 1, v224
	v_ashrrev_i32_e32 v213, 31, v212
	v_mov_b64_e32 v[110:111], s[68:69]
	s_movk_i32 s68, 0x2c00
	v_mad_i64_i32 v[110:111], s[68:69], v132, s68, v[110:111]
	v_lshl_add_u64 v[110:111], v[212:213], 2, v[110:111]
	global_store_dwordx4 v[110:111], v[90:93], off
	global_store_dwordx4 v[110:111], v[34:37], off offset:16

.LBB0_461:
	s_andn2_saveexec_b64 s[24:25], s[24:25]
	s_or_b64 exec, exec, s[24:25]
	s_mul_i32 s24, s56, 0x8400
	s_waitcnt lgkmcnt(0)
	s_add_u32 s24, s28, s24
	s_mul_hi_u32 s25, s56, 0x8400
	s_addc_u32 s25, s29, s25
	s_mul_i32 s28, s56, 0x2c00
	s_add_u32 s28, s30, s28
	s_mul_hi_u32 s29, s56, 0x2c00
	v_lshlrev_b64 v[110:111], 2, v[212:213]
	s_addc_u32 s29, s31, s29
	v_lshl_add_u64 v[216:217], s[24:25], 0, v[110:111]
	v_lshl_add_u64 v[214:215], s[28:29], 0, v[110:111]
	v_add_co_u32_e32 v110, vcc, 0x2000, v216
	s_waitcnt lgkmcnt(0)
	s_barrier
	v_mov_b32_e32 v250, 0x21008
	ds_read_b32 v250, v250
	s_waitcnt lgkmcnt(0)
	v_readfirstlane_b32 s101, v250
	s_add_i32 s101, s101, 64
	s_lshl_b32 s101, s101, 3
	s_and_b32 s32, s2, 7
	s_or_b32 s101, s101, s32
	s_nop 0
	v_addc_co_u32_e32 v111, vcc, 0, v217, vcc
	v_add_co_u32_e32 v124, vcc, 0x5000, v216
	global_load_dwordx4 v[120:123], v[216:217], off
	s_nop 0
	v_addc_co_u32_e32 v125, vcc, 0, v217, vcc
	global_load_dwordx4 v[128:131], v[110:111], off offset:3072
	s_nop 0
	global_load_dwordx4 v[124:127], v[124:125], off offset:2048
	s_nop 0
	global_load_dwordx4 v[132:135], v[214:215], off
	v_mov_b32_e32 v158, 0
	v_mov_b32_e32 v180, 0
	v_mov_b32_e32 v181, 0
	v_mov_b32_e32 v182, 0
	v_mov_b32_e32 v183, 0
	v_mov_b32_e32 v176, 0
	v_mov_b32_e32 v177, 0
	v_mov_b32_e32 v178, 0
	v_mov_b32_e32 v179, 0
	s_and_saveexec_b64 s[24:25], s[86:87]
	s_cbranch_execz .LBB0_463
	ds_read_b128 v[176:179], v228
	ds_read_b128 v[180:183], v225
